# grid barrier: an XCC leader releases its followers before doing its own cache invalidate
# baseline (speedup 1.0000x reference)
; DI unsigned xb_add(unsigned* p, unsigned v) { return __hip_atomic_fetch_add(p, v, __ATOMIC_RELAXED, __HIP_MEMORY_SCOPE_AGENT); }
; DI void xcd_barrier(const XcdBarrier& b) {
;     ...
;       __builtin_amdgcn_fence(__ATOMIC_ACQUIRE, "agent");
;       xb_add(&bar[XB_XGEN(b.x)], 1u);
;       asm volatile("s_waitcnt vmcnt(0)" ::: "memory");
.LBB0_860:
	s_or_b64 exec, exec, s[4:5]
	s_mov_b64 s[4:5], exec
	v_mbcnt_lo_u32_b32 v0, s4, 0
	v_mbcnt_hi_u32_b32 v0, s5, v0
	v_cmp_eq_u32_e32 vcc, 0, v0
	s_waitcnt vmcnt(0)
	s_and_saveexec_b64 s[8:9], vcc
	s_cbranch_execz .LBB0_862
	s_bcnt1_i32_b64 s4, s[4:5]
	v_mov_b32_e32 v0, s4
	v_readlane_b32 s4, v254, 59
	v_readlane_b32 s5, v254, 60
	s_nop 4
	global_atomic_add v1, v0, s[4:5]
.LBB0_862:
	s_or_b64 exec, exec, s[8:9]
	buffer_inv sc1
	s_waitcnt vmcnt(0)
